# plus phase-start table loads overlapped and in-proj row-scale table deferred past the first operand loads
# speedup vs baseline: 1.0262x; 1.0019x over previous
; #define LAS __attribute__((address_space(3)))
; __device__ __forceinline__ float frsq(float x) { return __builtin_amdgcn_rsqf(x); }
; #define PG8_STAGE(bufoff, gbase, voff) do { _Pragma("unroll") for (int _i = 0; _i < 2; ++_i) \
;         __builtin_amdgcn_global_load_lds((const unsigned*)((const char*)(gbase) + (voff)[_i]), (LAS unsigned*)(lds + (bufoff) + ldsw + _i * 8192), 16, 0, 0); } while (0)
; #define PG8_WAIT_V(n) asm volatile("s_waitcnt vmcnt(" #n ")" ::: "memory")
; #define PG8_BAR __builtin_amdgcn_s_barrier()
; template <class Epi, class Sched>
; __device__ __forceinline__ void gemm_phase(LAS unsigned char* lds, const Gemm g, const Sched& S, const Epi& E) {
;     ...
;     const char* cA = (const char*)g.A + (size_t)cur.pm * tstepA; const char* cB = (const char*)g.Bt + (size_t)cur.pn * tstepB;
;     PG8_STAGE(PG8_SB(0, 0), cB, voffB); PG8_STAGE(PG8_SB(0, 1), cB + hstepB, voffB); PG8_STAGE(PG8_SA(0, 0), cA, voffA); PG8_STAGE(PG8_SA(0, 1), cA + hstepA, voffA);
;     if (wr == 1) PG8_BAR;
;     PG8_WAIT_V(2); PG8_BAR;
;     PG8_STAGE(PG8_SB(1, 0), cB + kstep, voffB); PG8_STAGE(PG8_SA(1, 0), cA + kstep, voffA); PG8_STAGE(PG8_SB(1, 1), cB + hstepB + kstep, voffB);
;     PG8_WAIT_V(6); PG8_BAR;
; __global__ void __launch_bounds__(512) hymba_fwd(Args a) {
;     ...
;                 pg8::Unit u0; if (S.next(0, u0) && threadIdx.x < 256) { const float* rss = (const float*)(a.ws + WS_RSS) + u0.pm * 256 + threadIdx.x;
;                     ((LAS float*)(lds + 131072))[threadIdx.x] = frsq(((rss[0] + rss[NTOK]) + (rss[2 * NTOK] + rss[3 * NTOK])) * (1.f / 1024.f) + EPS); }
.LBB0_255:
	v_and_b32_e32 v160, 15, v10
	v_lshrrev_b32_e32 v10, 1, v10
	v_readlane_b32 s18, v244, 31
	v_and_b32_e32 v161, 24, v10
	s_lshl_b32 s16, s16, 5
	v_mov_b32_e32 v135, v145
	v_readlane_b32 s19, v244, 32
	v_lshlrev_b32_e32 v10, 1, v161
	v_lshlrev_b32_e32 v11, 2, v160
	s_and_b32 s36, s16, 0x60
	s_add_i32 m0, s8, 0x18000
	v_lshl_add_u64 v[0:1], v[0:1], 0, s[0:1]
	v_lshl_add_u64 v[12:13], s[18:19], 0, v[134:135]
	v_mov_b32_e32 v131, v145
	s_lshl_b32 s35, s5, 6
	v_lshl_or_b32 v10, v160, 6, v10
	s_lshl_b32 s17, s5, 13
	v_and_b32_e32 v16, 32, v11
	s_lshl_b32 s16, s36, 7
	s_waitcnt vmcnt(2)
	s_barrier
	global_load_lds_dwordx4 v[0:1], off
	v_lshl_add_u64 v[0:1], v[2:3], 0, s[0:1]
	s_add_i32 m0, s8, 0x1a000
	s_add_i32 s37, s8, 0x8000
	s_add_i32 s38, s8, 0xa000
	v_lshl_add_u64 v[14:15], s[18:19], 0, v[130:131]
	v_bitop3_b32 v162, v10, s16, v16 bitop3:0xde
	global_load_lds_dwordx4 v[0:1], off
	v_lshl_add_u64 v[0:1], v[12:13], 0, s[0:1]
	s_mov_b32 m0, s37
	s_add_u32 s16, s14, 0x40080
	v_bitop3_b32 v17, v10, s17, v16 bitop3:0xde
	global_load_lds_dwordx4 v[0:1], off
	v_lshl_add_u64 v[0:1], v[14:15], 0, s[0:1]
	s_mov_b32 m0, s38
	s_addc_u32 s17, s15, 0
	global_load_lds_dwordx4 v[0:1], off
	s_add_i32 m0, s8, 0x1c000
	v_lshl_add_u64 v[0:1], s[16:17], 0, v[132:133]
	global_load_lds_dwordx4 v[0:1], off
	v_lshl_add_u64 v[0:1], s[16:17], 0, v[128:129]
	s_add_i32 m0, s8, 0x1e000
	s_cmpk_lt_u32 s4, 0x100
	global_load_lds_dwordx4 v[0:1], off
	v_lshlrev_b32_e32 v0, 14, v8
	v_and_b32_e32 v0, 0xffff8000, v0
	v_lshl_add_u32 v0, v7, 11, v0
	v_and_b32_e32 v1, 1, v8
	v_lshl_or_b32 v0, v1, 6, v0
	v_lshl_add_u32 v136, v9, 1, v0
	v_lshlrev_b32_e32 v0, 14, v4
	s_cselect_b64 s[50:51], -1, 0
	s_lshl_b32 s4, s5, 8
	v_and_b32_e32 v0, 0xffff8000, v0
	s_waitcnt vmcnt(6)
	s_mov_b64 s[52:53], exec
	v_cmp_gt_u32_e32 vcc, 0x100, v178
	s_and_b64 exec, s[52:53], vcc
	v_add_f32_e32 v242, v242, v243
	v_add_f32_e32 v247, v247, v165
	s_nop 0
	v_add_f32_e32 v242, v242, v247
	s_nop 0
	v_fmamk_f32 v242, v242, 0x3a800000, v186
	s_nop 0
	v_rsq_f32_e32 v242, v242
	s_nop 1
	ds_write_b32 v184, v242
	s_mov_b64 exec, s[52:53]
	s_add_i32 s4, s4, 0
	v_lshl_add_u32 v0, v5, 11, v0
	v_and_b32_e32 v1, 1, v4
	v_readlane_b32 s16, v244, 27
	s_add_i32 s4, s4, 0x20000
	v_lshl_or_b32 v0, v1, 6, v0
	v_readlane_b32 s17, v244, 28
	v_add_u32_e32 v163, s4, v11
	v_mov_b32_e32 v137, v145
	v_lshl_add_u32 v138, v6, 1, v0
	v_mov_b32_e32 v139, v145
	s_mov_b32 s4, 0
	v_add_u32_e32 v164, 0, v17
	v_readlane_b32 s39, v244, 10
	s_mov_b32 s5, s16
	s_mov_b64 s[16:17], s[18:19]
	s_barrier
	s_waitcnt vmcnt(0)
	s_branch .LBB0_258

; #define LAS __attribute__((address_space(3)))
; __global__ void __launch_bounds__(512) hymba_fwd(Args a) {
;     ...
;                 if (tid < 128) ((LAS float*)(lds + 68608))[tid] = (tid < 64) ? a.mqn[l * 64 + tid] : a.mkn[l * 64 + tid - 64];
;                 if (tid < 512) ((LAS float*)(lds + 106496))[tid] = ((const float*)(a.ws + WS_LB))[l * 512 + tid];
;                 __syncthreads();
;                 { PrepIn cur; int u = wb; moba_prep_load(a, tid, u < 512 ? u : 0, cur);
;                   for (; u < 512; u += WG) { PrepIn nxt; moba_prep_unit(a, l, lds, tid, u, cur, nxt, (u + WG < 512) ? u + WG : u); cur = nxt; } }
.LBB0_424:
	s_or_b64 exec, exec, s[14:15]
	s_movk_i32 s4, 0x80
	v_cmp_gt_i32_e32 vcc, s4, v96
	s_and_saveexec_b64 s[14:15], vcc
	ds_write_b32 v241, v240
	s_or_b64 exec, exec, s[14:15]
	v_readlane_b32 s4, v245, 32
	v_readlane_b32 s5, v245, 33
	s_andn2_b64 vcc, exec, s[4:5]
	v_lshlrev_b32_e32 v124, 5, v96
	v_ashrrev_i32_e32 v97, 31, v96
	s_waitcnt lgkmcnt(0)
	s_barrier
	s_cbranch_vccnz .LBB0_435
	v_ashrrev_i32_e32 v98, 1, v96
	v_lshlrev_b32_e32 v196, 6, v96
	v_add_u32_e32 v196, 0x11000, v196
	v_and_b32_e32 v199, 63, v96
	v_lshrrev_b32_e32 v198, 6, v96
	v_lshlrev_b32_e32 v197, 4, v199
	v_lshl_or_b32 v197, v198, 12, v197
	v_add_u32_e32 v197, 0x11000, v197
	v_lshrrev_b32_e32 v201, 3, v199
	v_and_b32_e32 v200, 7, v199
	v_lshlrev_b32_e32 v200, 4, v200
	v_lshl_or_b32 v200, v201, 13, v200
	v_lshlrev_b32_e32 v199, 4, v199
	v_add_u32_e32 v201, 0x10000, v200
	v_add_u32_e32 v202, 0x20000, v200
	v_add_u32_e32 v203, 0x30000, v200
	v_readlane_b32 s4, v244, 8
	v_ashrrev_i32_e32 v99, 31, v98
	v_readlane_b32 s5, v244, 9
	v_and_b32_e32 v0, 32, v124
	v_lshlrev_b32_e32 v144, 1, v0
	v_lshl_add_u64 v[2:3], v[98:99], 0, s[4:5]
	v_readlane_b32 s4, v245, 34
	v_readlane_b32 s5, v245, 35
	v_and_b32_e32 v1, 1, v96
	v_lshlrev_b32_e32 v100, 5, v1
	v_lshl_add_u64 v[4:5], v[2:3], 0, s[4:5]
	v_readlane_b32 s4, v245, 40
	v_lshlrev_b64 v[6:7], 6, v[4:5]
	v_readlane_b32 s5, v245, 41
	v_lshlrev_b64 v[2:3], 7, v[2:3]
	v_cmp_eq_u32_e64 s[44:45], 0, v1
	v_lshl_add_u64 v[6:7], s[4:5], 0, v[6:7]
	v_readlane_b32 s4, v245, 38
	v_readlane_b32 s5, v245, 39
	global_load_dwordx4 v[48:51], v[6:7], off offset:48
	global_load_dwordx4 v[52:55], v[6:7], off offset:16
	global_load_dwordx4 v[56:59], v[6:7], off
	global_load_dwordx4 v[60:63], v[6:7], off offset:32
	v_lshl_add_u64 v[2:3], s[4:5], 0, v[2:3]
	v_lshl_add_u64 v[2:3], v[2:3], 0, v[144:145]
	v_readlane_b32 s4, v245, 36
	global_load_dwordx4 v[64:67], v[2:3], off offset:48
	global_load_dwordx4 v[68:71], v[2:3], off offset:32
	global_load_dwordx4 v[72:75], v[2:3], off offset:16
	global_load_dwordx4 v[76:79], v[2:3], off
	v_lshlrev_b64 v[2:3], 13, v[4:5]
	v_readlane_b32 s5, v245, 37
	v_lshrrev_b32_e32 v4, 5, v98
	v_cmp_gt_i32_e64 s[46:47], 64, v96
	v_lshl_add_u64 v[2:3], s[4:5], 0, v[2:3]
	v_lshl_add_u64 v[2:3], v[2:3], 0, v[144:145]
	global_load_dwordx4 v[80:83], v[2:3], off offset:48
	global_load_dwordx4 v[84:87], v[2:3], off offset:32
	global_load_dwordx4 v[88:91], v[2:3], off offset:16
	global_load_dwordx4 v[92:95], v[2:3], off
	s_add_i32 s4, 0, 0x10c00
	v_lshlrev_b32_e32 v2, 7, v1
	v_add_u32_e32 v125, s4, v2
	s_movk_i32 s4, 0x104
	v_add_u32_e32 v1, 0, v2
	v_mul_lo_u32 v2, v98, s4
	v_readlane_b32 s4, v244, 50
	v_and_b32_e32 v3, 63, v96
	v_lshlrev_b32_e32 v3, 2, v3
	v_lshl_add_u32 v126, v96, 2, s4
	s_movk_i32 s4, 0x2080
	v_mul_lo_u32 v4, v4, s4
	v_add3_u32 v127, v4, v3, 0
	v_lshlrev_b32_e32 v102, 1, v0
	v_add_u32_e32 v128, v1, v2
	v_readlane_b32 s5, v245, 44
	v_readlane_b32 s98, v244, 36
	s_movk_i32 s99, 0x200
	s_cmp_eq_u32 s3, 0x100
	s_cbranch_scc0 .Lrm_pp
	s_and_b32 s99, s2, 7
	s_add_i32 s99, s99, 1
	s_lshl_b32 s99, s99, 6
	s_mov_b32 s98, 28

; #define LAS __attribute__((address_space(3)))
; __device__ __forceinline__ int otid() { int t = threadIdx.x; asm volatile("" : "+v"(t)); return t; }
; __global__ void __launch_bounds__(512) hymba_fwd(Args a) {
;     ...
;             { const int tid = otid();
;               if (tid < 512) ((LAS float*)(lds + 106496))[tid] = ((const float*)(a.ws + WS_LB))[l * 512 + tid];
;               if (tid < 128) ((LAS float*)(lds + 106496 + 2048))[tid] = a.hon[l * 128 + tid];
;               __syncthreads();
.LBB0_641:
	s_or_b64 exec, exec, s[14:15]
	s_waitcnt vmcnt(0)
	ds_write_b32 v241, v240
	v_readlane_b32 s4, v245, 56
	v_readlane_b32 s5, v245, 57
	s_andn2_b64 vcc, exec, s[4:5]
	s_waitcnt lgkmcnt(0)
	s_barrier
	s_cbranch_vccnz .LBB0_680
	v_add_u32_e32 v0, 0x200, v121
	v_ashrrev_i32_e32 v118, 4, v0
	v_readlane_b32 s4, v245, 58
	v_ashrrev_i32_e32 v119, 31, v118
	v_readlane_b32 s5, v245, 59
	v_lshlrev_b32_e32 v9, 3, v121
	v_ashrrev_i32_e32 v116, 4, v121
	v_lshl_add_u64 v[0:1], s[4:5], 0, v[118:119]
	v_readlane_b32 s8, v245, 60
	v_and_b32_e32 v8, 0x78, v9
	v_ashrrev_i32_e32 v117, 31, v116
	v_lshlrev_b64 v[0:1], 13, v[0:1]
	v_readlane_b32 s9, v245, 61
	v_lshlrev_b32_e32 v144, 1, v8
	v_lshl_add_u64 v[6:7], s[4:5], 0, v[116:117]
	v_lshl_add_u64 v[0:1], s[8:9], 0, v[0:1]
	v_lshl_add_u64 v[0:1], v[0:1], 0, v[144:145]
	v_lshlrev_b64 v[6:7], 13, v[6:7]
	v_add_co_u32_e32 v4, vcc, s26, v0
	v_lshl_add_u64 v[6:7], s[8:9], 0, v[6:7]
	s_nop 0
	v_addc_co_u32_e32 v5, vcc, 0, v1, vcc
	v_lshl_add_u64 v[6:7], v[6:7], 0, v[144:145]
	global_load_dwordx4 v[28:31], v[0:1], off offset:1024
	s_nop 0
	global_load_dwordx4 v[0:3], v[4:5], off offset:2048
	global_load_dwordx4 v[24:27], v[4:5], off offset:3072
	global_load_dwordx4 v[100:103], v[6:7], off offset:1024
	v_add_co_u32_e32 v4, vcc, s26, v6
	v_bfe_u32 v11, v121, 4, 2
	s_nop 0
	v_addc_co_u32_e32 v5, vcc, 0, v7, vcc
	global_load_dwordx4 v[72:75], v[4:5], off offset:3072
	s_nop 0
	global_load_dwordx4 v[4:7], v[4:5], off offset:2048
	v_lshlrev_b32_e32 v122, 2, v11
	s_add_i32 s4, 0, 0x1a000
	v_lshlrev_b32_e32 v10, 2, v8
	v_and_b32_e32 v120, 15, v121
	v_or_b32_e32 v32, 2, v122
	v_add_u32_e32 v170, s4, v10
	v_add_u32_e32 v171, 0, v10
	v_lshlrev_b32_e32 v10, 5, v121
	v_and_b32_e32 v12, 0x7f, v121
	v_readlane_b32 s4, v244, 53
	v_cmp_gt_u32_e64 s[52:53], v32, v120
	v_or_b32_e32 v32, 3, v122
	v_and_b32_e32 v10, 0xfffffe00, v10
	v_ashrrev_i32_e32 v13, 7, v121
	v_lshl_add_u32 v174, v12, 2, 0
	v_readlane_b32 s5, v244, 54
	v_lshlrev_b32_e32 v17, 4, v11
	v_mov_b32_e32 v21, s4
	v_cmp_gt_u32_e64 s[54:55], v32, v120
	v_bfe_u32 v32, v121, 2, 2
	v_add_u32_e32 v172, v171, v10
	v_lshlrev_b32_e32 v10, 3, v11
	v_lshl_add_u32 v175, v13, 13, v174
	v_cmp_lt_i32_e64 s[42:43], 0, v13
	v_cmp_lt_i32_e64 s[44:45], 1, v13
	v_cmp_lt_i32_e64 s[46:47], 2, v13
	v_add_u32_e32 v177, s4, v144
	v_add_u32_e32 v12, s5, v144
	v_lshlrev_b32_e32 v13, 9, v116
	v_mul_lo_u32 v14, v116, s27
	v_lshlrev_b32_e32 v15, 9, v118
	v_mul_lo_u32 v16, v118, s27
	v_add_u32_e32 v18, s4, v17
	v_mul_u32_u24_e32 v19, 0x110, v120
	v_or_b32_e32 v20, 64, v17
	v_mad_u32_u24 v21, v120, s31, v21
	v_or_b32_e32 v22, 0x80, v17
	v_or_b32_e32 v23, 0xc0, v17
	v_and_b32_e32 v182, 24, v9
	v_or_b32_e32 v9, v122, v32
	v_mov_b32_e32 v32, s5
	v_readlane_b32 s4, v244, 55
	v_lshlrev_b32_e32 v173, 7, v120
	v_sub_u32_e32 v176, v171, v144
	v_mul_lo_u32 v180, v116, s31
	v_mul_lo_u32 v181, v118, s31
	v_cmp_gt_u32_e64 s[48:49], v122, v120
	v_cmp_ge_u32_e64 s[50:51], v122, v120
	v_mad_u32_u24 v183, v9, s27, v32
	v_add_u32_e32 v195, 0, v17
	v_cmp_eq_u32_e64 s[56:57], 0, v11
	v_lshl_add_u32 v196, v120, 2, s4
	v_lshlrev_b32_e32 v144, 1, v10
	v_lshlrev_b32_e32 v124, 1, v8
	v_add_u32_e32 v197, v171, v13
	v_add_u32_e32 v198, v12, v14
	v_add_u32_e32 v199, v171, v15
	v_add_u32_e32 v200, v12, v16
	v_add_u32_e32 v201, v18, v19
	v_add_u32_e32 v202, v21, v20
	v_add_u32_e32 v203, v21, v22
	v_add_u32_e32 v204, v21, v23
	s_mov_b32 s8, s2
	s_mov_b32 s98, s3
	s_movk_i32 s99, 0x400
	s_cmp_eq_u32 s3, 0x100
	s_cbranch_scc0 .Lrm_s3
	s_and_b32 s8, s2, 7
	s_lshl_b32 s8, s8, 7
	s_add_i32 s99, s8, 0x80
	s_lshr_b32 s98, s2, 3
	s_or_b32 s8, s8, s98
	s_mov_b32 s98, 32
